# up_proj epilogue: gate exp/rcp interleaved with the independent DPP taps of the up half (same arithmetic order per register)
# baseline (speedup 1.0000x reference)
.Leu_pv0_skip_n0:
	s_cmp_eq_u32 s63, 0
	s_movk_i32 s40, 0x1000
	s_cselect_b32 s39, 0x800, s40
	s_add_i32 s39, s39, s67
	v_add_u32_e32 v59, s39, v217
	s_and_saveexec_b64 s[8:9], s[10:11]
	ds_read_b128 v[204:207], v59 offset:0
	ds_read_b128 v[208:211], v59 offset:128
	s_mov_b64 exec, s[8:9]
	s_waitcnt lgkmcnt(0)
	v_pk_fma_f32 v[44:45], v[112:113], v[192:193], v[120:121]
	v_pk_fma_f32 v[46:47], v[114:115], v[194:195], v[122:123]
	v_pk_fma_f32 v[48:49], v[108:109], v[180:181], v[116:117]
	v_pk_fma_f32 v[50:51], v[110:111], v[182:183], v[118:119]
	v_fmac_f32_dpp v44, v192, v104 row_shr:1 row_mask:0xf bank_mask:0xf
	v_fmac_f32_dpp v45, v193, v105 row_shr:1 row_mask:0xf bank_mask:0xf
	v_fmac_f32_dpp v46, v194, v106 row_shr:1 row_mask:0xf bank_mask:0xf
	v_fmac_f32_dpp v47, v195, v107 row_shr:1 row_mask:0xf bank_mask:0xf
	v_fmac_f32_dpp v44, v192, v100 row_shr:2 row_mask:0xf bank_mask:0xf
	v_fmac_f32_dpp v45, v193, v101 row_shr:2 row_mask:0xf bank_mask:0xf
	v_fmac_f32_dpp v46, v194, v102 row_shr:2 row_mask:0xf bank_mask:0xf
	v_fmac_f32_dpp v47, v195, v103 row_shr:2 row_mask:0xf bank_mask:0xf
	v_fmac_f32_dpp v44, v196, v28 row_ror:1 row_mask:0xf bank_mask:0xf
	v_fmac_f32_dpp v45, v197, v29 row_ror:1 row_mask:0xf bank_mask:0xf
	v_fmac_f32_dpp v46, v198, v30 row_ror:1 row_mask:0xf bank_mask:0xf
	v_fmac_f32_dpp v47, v199, v31 row_ror:1 row_mask:0xf bank_mask:0xf
	v_fmac_f32_dpp v44, v196, v32 row_ror:2 row_mask:0xf bank_mask:0xf
	v_fmac_f32_dpp v45, v197, v33 row_ror:2 row_mask:0xf bank_mask:0xf
	v_fmac_f32_dpp v46, v198, v34 row_ror:2 row_mask:0xf bank_mask:0xf
	v_fmac_f32_dpp v47, v199, v35 row_ror:2 row_mask:0xf bank_mask:0xf
	v_pk_mul_f32 v[52:53], v[44:45], v[240:241] op_sel_hi:[1,0]
	v_pk_mul_f32 v[54:55], v[46:47], v[240:241] op_sel_hi:[1,0]
	v_exp_f32_e32 v52, v52
	v_fmac_f32_dpp v48, v180, v96 row_shr:1 row_mask:0xf bank_mask:0xf
	v_fmac_f32_dpp v49, v181, v97 row_shr:1 row_mask:0xf bank_mask:0xf
	v_exp_f32_e32 v53, v53
	v_fmac_f32_dpp v50, v182, v98 row_shr:1 row_mask:0xf bank_mask:0xf
	v_fmac_f32_dpp v51, v183, v99 row_shr:1 row_mask:0xf bank_mask:0xf
	v_exp_f32_e32 v54, v54
	v_fmac_f32_dpp v48, v180, v92 row_shr:2 row_mask:0xf bank_mask:0xf
	v_fmac_f32_dpp v49, v181, v93 row_shr:2 row_mask:0xf bank_mask:0xf
	v_exp_f32_e32 v55, v55
	v_fmac_f32_dpp v50, v182, v94 row_shr:2 row_mask:0xf bank_mask:0xf
	v_fmac_f32_dpp v51, v183, v95 row_shr:2 row_mask:0xf bank_mask:0xf
	v_pk_add_f32 v[52:53], v[52:53], v[240:241] op_sel:[0,1] op_sel_hi:[1,1]
	v_pk_add_f32 v[54:55], v[54:55], v[240:241] op_sel:[0,1] op_sel_hi:[1,1]
	v_rcp_f32_e32 v52, v52
	v_fmac_f32_dpp v48, v200, v36 row_ror:1 row_mask:0xf bank_mask:0xf
	v_fmac_f32_dpp v49, v201, v37 row_ror:1 row_mask:0xf bank_mask:0xf
	v_rcp_f32_e32 v53, v53
	v_fmac_f32_dpp v50, v202, v38 row_ror:1 row_mask:0xf bank_mask:0xf
	v_fmac_f32_dpp v51, v203, v39 row_ror:1 row_mask:0xf bank_mask:0xf
	v_rcp_f32_e32 v54, v54
	v_fmac_f32_dpp v48, v200, v40 row_ror:2 row_mask:0xf bank_mask:0xf
	v_fmac_f32_dpp v49, v201, v41 row_ror:2 row_mask:0xf bank_mask:0xf
	v_rcp_f32_e32 v55, v55
	v_fmac_f32_dpp v50, v202, v42 row_ror:2 row_mask:0xf bank_mask:0xf
	v_fmac_f32_dpp v51, v203, v43 row_ror:2 row_mask:0xf bank_mask:0xf
	v_pk_mul_f32 v[44:45], v[44:45], v[52:53]
	v_pk_mul_f32 v[46:47], v[46:47], v[54:55]
	v_pk_mul_f32 v[44:45], v[48:49], v[44:45]
	v_pk_mul_f32 v[46:47], v[50:51], v[46:47]
	v_cvt_pk_bf16_f32 v242, v44, v45
	v_cvt_pk_bf16_f32 v243, v46, v47
	s_cmp_lg_u32 s63, 0
	s_cbranch_scc1 .Leu_halo_skip_a0n0
	v_mul_u32_u24_e32 v58, 0xb000, v56
	v_lshl_add_u32 v58, v57, 5, v58
	s_mul_i32 s39, s12, 0x2c000
	s_lshl_b32 s40, s13, 9
	s_add_i32 s39, s39, s40
	s_lshl_b32 s40, s64, 2
	s_add_i32 s39, s39, s40
	s_add_u32 s20, s72, s39
	s_addc_u32 s21, s73, 0
	s_add_u32 s22, s20, 0x5800
	s_addc_u32 s23, s21, 0
	s_and_saveexec_b64 s[8:9], s[14:15]
	global_store_dwordx4 v58, v[192:195], s[20:21]
	global_store_dwordx4 v58, v[180:183], s[22:23]
	s_mov_b64 exec, s[8:9]
.Leu_halo_skip_a0n0:
	v_pk_fma_f32 v[44:45], v[112:113], v[188:189], v[120:121]
	v_pk_fma_f32 v[46:47], v[114:115], v[190:191], v[122:123]
	v_pk_fma_f32 v[48:49], v[108:109], v[184:185], v[116:117]
	v_pk_fma_f32 v[50:51], v[110:111], v[186:187], v[118:119]
	v_fmac_f32_dpp v44, v188, v104 row_shr:1 row_mask:0xf bank_mask:0xf
	v_fmac_f32_dpp v45, v189, v105 row_shr:1 row_mask:0xf bank_mask:0xf
	v_fmac_f32_dpp v46, v190, v106 row_shr:1 row_mask:0xf bank_mask:0xf
	v_fmac_f32_dpp v47, v191, v107 row_shr:1 row_mask:0xf bank_mask:0xf
	v_fmac_f32_dpp v44, v188, v100 row_shr:2 row_mask:0xf bank_mask:0xf
	v_fmac_f32_dpp v45, v189, v101 row_shr:2 row_mask:0xf bank_mask:0xf
	v_fmac_f32_dpp v46, v190, v102 row_shr:2 row_mask:0xf bank_mask:0xf
	v_fmac_f32_dpp v47, v191, v103 row_shr:2 row_mask:0xf bank_mask:0xf
	v_fmac_f32_dpp v44, v192, v28 row_ror:1 row_mask:0xf bank_mask:0xf
	v_fmac_f32_dpp v45, v193, v29 row_ror:1 row_mask:0xf bank_mask:0xf
	v_fmac_f32_dpp v46, v194, v30 row_ror:1 row_mask:0xf bank_mask:0xf
	v_fmac_f32_dpp v47, v195, v31 row_ror:1 row_mask:0xf bank_mask:0xf
	v_fmac_f32_dpp v44, v192, v32 row_ror:2 row_mask:0xf bank_mask:0xf
	v_fmac_f32_dpp v45, v193, v33 row_ror:2 row_mask:0xf bank_mask:0xf
	v_fmac_f32_dpp v46, v194, v34 row_ror:2 row_mask:0xf bank_mask:0xf
	v_fmac_f32_dpp v47, v195, v35 row_ror:2 row_mask:0xf bank_mask:0xf
	v_pk_mul_f32 v[52:53], v[44:45], v[240:241] op_sel_hi:[1,0]
	v_pk_mul_f32 v[54:55], v[46:47], v[240:241] op_sel_hi:[1,0]
	v_exp_f32_e32 v52, v52
	v_fmac_f32_dpp v48, v184, v96 row_shr:1 row_mask:0xf bank_mask:0xf
	v_fmac_f32_dpp v49, v185, v97 row_shr:1 row_mask:0xf bank_mask:0xf
	v_exp_f32_e32 v53, v53
	v_fmac_f32_dpp v50, v186, v98 row_shr:1 row_mask:0xf bank_mask:0xf
	v_fmac_f32_dpp v51, v187, v99 row_shr:1 row_mask:0xf bank_mask:0xf
	v_exp_f32_e32 v54, v54
	v_fmac_f32_dpp v48, v184, v92 row_shr:2 row_mask:0xf bank_mask:0xf
	v_fmac_f32_dpp v49, v185, v93 row_shr:2 row_mask:0xf bank_mask:0xf
	v_exp_f32_e32 v55, v55
	v_fmac_f32_dpp v50, v186, v94 row_shr:2 row_mask:0xf bank_mask:0xf
	v_fmac_f32_dpp v51, v187, v95 row_shr:2 row_mask:0xf bank_mask:0xf
	v_pk_add_f32 v[52:53], v[52:53], v[240:241] op_sel:[0,1] op_sel_hi:[1,1]
	v_pk_add_f32 v[54:55], v[54:55], v[240:241] op_sel:[0,1] op_sel_hi:[1,1]
	v_rcp_f32_e32 v52, v52
	v_fmac_f32_dpp v48, v180, v36 row_ror:1 row_mask:0xf bank_mask:0xf
	v_fmac_f32_dpp v49, v181, v37 row_ror:1 row_mask:0xf bank_mask:0xf
	v_rcp_f32_e32 v53, v53
	v_fmac_f32_dpp v50, v182, v38 row_ror:1 row_mask:0xf bank_mask:0xf
	v_fmac_f32_dpp v51, v183, v39 row_ror:1 row_mask:0xf bank_mask:0xf
	v_rcp_f32_e32 v54, v54
	v_fmac_f32_dpp v48, v180, v40 row_ror:2 row_mask:0xf bank_mask:0xf
	v_fmac_f32_dpp v49, v181, v41 row_ror:2 row_mask:0xf bank_mask:0xf
	v_rcp_f32_e32 v55, v55
	v_fmac_f32_dpp v50, v182, v42 row_ror:2 row_mask:0xf bank_mask:0xf
	v_fmac_f32_dpp v51, v183, v43 row_ror:2 row_mask:0xf bank_mask:0xf
	v_pk_mul_f32 v[44:45], v[44:45], v[52:53]
	v_pk_mul_f32 v[46:47], v[46:47], v[54:55]
	v_pk_mul_f32 v[44:45], v[48:49], v[44:45]
	v_pk_mul_f32 v[46:47], v[50:51], v[46:47]
	v_cvt_pk_bf16_f32 v244, v44, v45
	v_cvt_pk_bf16_f32 v245, v46, v47
	v_pk_fma_f32 v[44:45], v[112:113], v[176:177], v[120:121]
	v_pk_fma_f32 v[46:47], v[114:115], v[178:179], v[122:123]
	v_pk_fma_f32 v[48:49], v[108:109], v[172:173], v[116:117]
	v_pk_fma_f32 v[50:51], v[110:111], v[174:175], v[118:119]
	v_fmac_f32_dpp v44, v176, v104 row_shr:1 row_mask:0xf bank_mask:0xf
	v_fmac_f32_dpp v45, v177, v105 row_shr:1 row_mask:0xf bank_mask:0xf
	v_fmac_f32_dpp v46, v178, v106 row_shr:1 row_mask:0xf bank_mask:0xf
	v_fmac_f32_dpp v47, v179, v107 row_shr:1 row_mask:0xf bank_mask:0xf
	v_fmac_f32_dpp v44, v176, v100 row_shr:2 row_mask:0xf bank_mask:0xf
	v_fmac_f32_dpp v45, v177, v101 row_shr:2 row_mask:0xf bank_mask:0xf
	v_fmac_f32_dpp v46, v178, v102 row_shr:2 row_mask:0xf bank_mask:0xf
	v_fmac_f32_dpp v47, v179, v103 row_shr:2 row_mask:0xf bank_mask:0xf
	v_fmac_f32_dpp v44, v188, v28 row_ror:1 row_mask:0xf bank_mask:0xf
	v_fmac_f32_dpp v45, v189, v29 row_ror:1 row_mask:0xf bank_mask:0xf
	v_fmac_f32_dpp v46, v190, v30 row_ror:1 row_mask:0xf bank_mask:0xf
	v_fmac_f32_dpp v47, v191, v31 row_ror:1 row_mask:0xf bank_mask:0xf
	v_fmac_f32_dpp v44, v188, v32 row_ror:2 row_mask:0xf bank_mask:0xf
	v_fmac_f32_dpp v45, v189, v33 row_ror:2 row_mask:0xf bank_mask:0xf
	v_fmac_f32_dpp v46, v190, v34 row_ror:2 row_mask:0xf bank_mask:0xf
	v_fmac_f32_dpp v47, v191, v35 row_ror:2 row_mask:0xf bank_mask:0xf
	v_pk_mul_f32 v[52:53], v[44:45], v[240:241] op_sel_hi:[1,0]
	v_pk_mul_f32 v[54:55], v[46:47], v[240:241] op_sel_hi:[1,0]
	v_exp_f32_e32 v52, v52
	v_fmac_f32_dpp v48, v172, v96 row_shr:1 row_mask:0xf bank_mask:0xf
	v_fmac_f32_dpp v49, v173, v97 row_shr:1 row_mask:0xf bank_mask:0xf
	v_exp_f32_e32 v53, v53
	v_fmac_f32_dpp v50, v174, v98 row_shr:1 row_mask:0xf bank_mask:0xf
	v_fmac_f32_dpp v51, v175, v99 row_shr:1 row_mask:0xf bank_mask:0xf
	v_exp_f32_e32 v54, v54
	v_fmac_f32_dpp v48, v172, v92 row_shr:2 row_mask:0xf bank_mask:0xf
	v_fmac_f32_dpp v49, v173, v93 row_shr:2 row_mask:0xf bank_mask:0xf
	v_exp_f32_e32 v55, v55
	v_fmac_f32_dpp v50, v174, v94 row_shr:2 row_mask:0xf bank_mask:0xf
	v_fmac_f32_dpp v51, v175, v95 row_shr:2 row_mask:0xf bank_mask:0xf
	v_pk_add_f32 v[52:53], v[52:53], v[240:241] op_sel:[0,1] op_sel_hi:[1,1]
	v_pk_add_f32 v[54:55], v[54:55], v[240:241] op_sel:[0,1] op_sel_hi:[1,1]
	v_rcp_f32_e32 v52, v52
	v_fmac_f32_dpp v48, v184, v36 row_ror:1 row_mask:0xf bank_mask:0xf
	v_fmac_f32_dpp v49, v185, v37 row_ror:1 row_mask:0xf bank_mask:0xf
	v_rcp_f32_e32 v53, v53
	v_fmac_f32_dpp v50, v186, v38 row_ror:1 row_mask:0xf bank_mask:0xf
	v_fmac_f32_dpp v51, v187, v39 row_ror:1 row_mask:0xf bank_mask:0xf
	v_rcp_f32_e32 v54, v54
	v_fmac_f32_dpp v48, v184, v40 row_ror:2 row_mask:0xf bank_mask:0xf
	v_fmac_f32_dpp v49, v185, v41 row_ror:2 row_mask:0xf bank_mask:0xf
	v_rcp_f32_e32 v55, v55
	v_fmac_f32_dpp v50, v186, v42 row_ror:2 row_mask:0xf bank_mask:0xf
	v_fmac_f32_dpp v51, v187, v43 row_ror:2 row_mask:0xf bank_mask:0xf
	v_pk_mul_f32 v[44:45], v[44:45], v[52:53]
	v_pk_mul_f32 v[46:47], v[46:47], v[54:55]
	v_pk_mul_f32 v[44:45], v[48:49], v[44:45]
	v_pk_mul_f32 v[46:47], v[50:51], v[46:47]
	v_cvt_pk_bf16_f32 v246, v44, v45
	v_cvt_pk_bf16_f32 v247, v46, v47
	v_pk_fma_f32 v[44:45], v[112:113], v[168:169], v[120:121]
	v_pk_fma_f32 v[46:47], v[114:115], v[170:171], v[122:123]
	v_pk_fma_f32 v[48:49], v[108:109], v[164:165], v[116:117]
	v_pk_fma_f32 v[50:51], v[110:111], v[166:167], v[118:119]
	v_fmac_f32_dpp v44, v168, v104 row_shr:1 row_mask:0xf bank_mask:0xf
	v_fmac_f32_dpp v45, v169, v105 row_shr:1 row_mask:0xf bank_mask:0xf
	v_fmac_f32_dpp v46, v170, v106 row_shr:1 row_mask:0xf bank_mask:0xf
	v_fmac_f32_dpp v47, v171, v107 row_shr:1 row_mask:0xf bank_mask:0xf
	v_fmac_f32_dpp v44, v168, v100 row_shr:2 row_mask:0xf bank_mask:0xf
	v_fmac_f32_dpp v45, v169, v101 row_shr:2 row_mask:0xf bank_mask:0xf
	v_fmac_f32_dpp v46, v170, v102 row_shr:2 row_mask:0xf bank_mask:0xf
	v_fmac_f32_dpp v47, v171, v103 row_shr:2 row_mask:0xf bank_mask:0xf
	v_fmac_f32_dpp v44, v176, v28 row_ror:1 row_mask:0xf bank_mask:0xf
	v_fmac_f32_dpp v45, v177, v29 row_ror:1 row_mask:0xf bank_mask:0xf
	v_fmac_f32_dpp v46, v178, v30 row_ror:1 row_mask:0xf bank_mask:0xf
	v_fmac_f32_dpp v47, v179, v31 row_ror:1 row_mask:0xf bank_mask:0xf
	v_fmac_f32_dpp v44, v176, v32 row_ror:2 row_mask:0xf bank_mask:0xf
	v_fmac_f32_dpp v45, v177, v33 row_ror:2 row_mask:0xf bank_mask:0xf
	v_fmac_f32_dpp v46, v178, v34 row_ror:2 row_mask:0xf bank_mask:0xf
	v_fmac_f32_dpp v47, v179, v35 row_ror:2 row_mask:0xf bank_mask:0xf
	v_pk_mul_f32 v[52:53], v[44:45], v[240:241] op_sel_hi:[1,0]
	v_pk_mul_f32 v[54:55], v[46:47], v[240:241] op_sel_hi:[1,0]
	v_exp_f32_e32 v52, v52
	v_fmac_f32_dpp v48, v164, v96 row_shr:1 row_mask:0xf bank_mask:0xf
	v_fmac_f32_dpp v49, v165, v97 row_shr:1 row_mask:0xf bank_mask:0xf
	v_exp_f32_e32 v53, v53
	v_fmac_f32_dpp v50, v166, v98 row_shr:1 row_mask:0xf bank_mask:0xf
	v_fmac_f32_dpp v51, v167, v99 row_shr:1 row_mask:0xf bank_mask:0xf
	v_exp_f32_e32 v54, v54
	v_fmac_f32_dpp v48, v164, v92 row_shr:2 row_mask:0xf bank_mask:0xf
	v_fmac_f32_dpp v49, v165, v93 row_shr:2 row_mask:0xf bank_mask:0xf
	v_exp_f32_e32 v55, v55
	v_fmac_f32_dpp v50, v166, v94 row_shr:2 row_mask:0xf bank_mask:0xf
	v_fmac_f32_dpp v51, v167, v95 row_shr:2 row_mask:0xf bank_mask:0xf
	v_pk_add_f32 v[52:53], v[52:53], v[240:241] op_sel:[0,1] op_sel_hi:[1,1]
	v_pk_add_f32 v[54:55], v[54:55], v[240:241] op_sel:[0,1] op_sel_hi:[1,1]
	v_rcp_f32_e32 v52, v52
	v_fmac_f32_dpp v48, v172, v36 row_ror:1 row_mask:0xf bank_mask:0xf
	v_fmac_f32_dpp v49, v173, v37 row_ror:1 row_mask:0xf bank_mask:0xf
	v_rcp_f32_e32 v53, v53
	v_fmac_f32_dpp v50, v174, v38 row_ror:1 row_mask:0xf bank_mask:0xf
	v_fmac_f32_dpp v51, v175, v39 row_ror:1 row_mask:0xf bank_mask:0xf
	v_rcp_f32_e32 v54, v54
	v_fmac_f32_dpp v48, v172, v40 row_ror:2 row_mask:0xf bank_mask:0xf
	v_fmac_f32_dpp v49, v173, v41 row_ror:2 row_mask:0xf bank_mask:0xf
	v_rcp_f32_e32 v55, v55
	v_fmac_f32_dpp v50, v174, v42 row_ror:2 row_mask:0xf bank_mask:0xf
	v_fmac_f32_dpp v51, v175, v43 row_ror:2 row_mask:0xf bank_mask:0xf
	v_pk_mul_f32 v[44:45], v[44:45], v[52:53]
	v_pk_mul_f32 v[46:47], v[46:47], v[54:55]
	v_pk_mul_f32 v[44:45], v[48:49], v[44:45]
	v_pk_mul_f32 v[46:47], v[50:51], v[46:47]
	v_cvt_pk_bf16_f32 v248, v44, v45
	v_cvt_pk_bf16_f32 v249, v46, v47
	global_load_dwordx4 v[236:239], v235, s[0:1] offset:16
	global_load_dwordx4 v[192:195], v235, s[30:31] offset:16
	global_load_dwordx4 v[180:183], v235, s[34:35] offset:16
	global_load_dwordx4 v[188:191], v235, s[2:3] offset:16
	global_load_dwordx4 v[184:187], v235, s[36:37] offset:16
	global_load_dwordx4 v[176:179], v235, s[48:49] offset:16
	global_load_dwordx4 v[172:175], v235, s[46:47] offset:16
	global_load_dwordx4 v[168:171], v235, s[44:45] offset:16
	v_pk_fma_f32 v[44:45], v[112:113], v[128:129], v[120:121]
	v_pk_fma_f32 v[46:47], v[114:115], v[130:131], v[122:123]
	v_pk_fma_f32 v[48:49], v[108:109], v[124:125], v[116:117]
	v_pk_fma_f32 v[50:51], v[110:111], v[126:127], v[118:119]
	v_fmac_f32_dpp v44, v128, v104 row_shr:1 row_mask:0xf bank_mask:0xf
	v_fmac_f32_dpp v45, v129, v105 row_shr:1 row_mask:0xf bank_mask:0xf
	v_fmac_f32_dpp v46, v130, v106 row_shr:1 row_mask:0xf bank_mask:0xf
	v_fmac_f32_dpp v47, v131, v107 row_shr:1 row_mask:0xf bank_mask:0xf
	v_fmac_f32_dpp v44, v128, v100 row_shr:2 row_mask:0xf bank_mask:0xf
	v_fmac_f32_dpp v45, v129, v101 row_shr:2 row_mask:0xf bank_mask:0xf
	v_fmac_f32_dpp v46, v130, v102 row_shr:2 row_mask:0xf bank_mask:0xf
	v_fmac_f32_dpp v47, v131, v103 row_shr:2 row_mask:0xf bank_mask:0xf
	v_fmac_f32_dpp v44, v204, v28 row_ror:1 row_mask:0xf bank_mask:0xf
	v_fmac_f32_dpp v45, v205, v29 row_ror:1 row_mask:0xf bank_mask:0xf
	v_fmac_f32_dpp v46, v206, v30 row_ror:1 row_mask:0xf bank_mask:0xf
	v_fmac_f32_dpp v47, v207, v31 row_ror:1 row_mask:0xf bank_mask:0xf
	v_fmac_f32_dpp v44, v204, v32 row_ror:2 row_mask:0xf bank_mask:0xf
	v_fmac_f32_dpp v45, v205, v33 row_ror:2 row_mask:0xf bank_mask:0xf
	v_fmac_f32_dpp v46, v206, v34 row_ror:2 row_mask:0xf bank_mask:0xf
	v_fmac_f32_dpp v47, v207, v35 row_ror:2 row_mask:0xf bank_mask:0xf
	v_pk_mul_f32 v[52:53], v[44:45], v[240:241] op_sel_hi:[1,0]
	v_pk_mul_f32 v[54:55], v[46:47], v[240:241] op_sel_hi:[1,0]
	v_exp_f32_e32 v52, v52
	v_fmac_f32_dpp v48, v124, v96 row_shr:1 row_mask:0xf bank_mask:0xf
	v_fmac_f32_dpp v49, v125, v97 row_shr:1 row_mask:0xf bank_mask:0xf
	v_exp_f32_e32 v53, v53
	v_fmac_f32_dpp v50, v126, v98 row_shr:1 row_mask:0xf bank_mask:0xf
	v_fmac_f32_dpp v51, v127, v99 row_shr:1 row_mask:0xf bank_mask:0xf
	v_exp_f32_e32 v54, v54
	v_fmac_f32_dpp v48, v124, v92 row_shr:2 row_mask:0xf bank_mask:0xf
	v_fmac_f32_dpp v49, v125, v93 row_shr:2 row_mask:0xf bank_mask:0xf
	v_exp_f32_e32 v55, v55
	v_fmac_f32_dpp v50, v126, v94 row_shr:2 row_mask:0xf bank_mask:0xf
	v_fmac_f32_dpp v51, v127, v95 row_shr:2 row_mask:0xf bank_mask:0xf
	v_pk_add_f32 v[52:53], v[52:53], v[240:241] op_sel:[0,1] op_sel_hi:[1,1]
	v_pk_add_f32 v[54:55], v[54:55], v[240:241] op_sel:[0,1] op_sel_hi:[1,1]
	v_rcp_f32_e32 v52, v52
	v_fmac_f32_dpp v48, v208, v36 row_ror:1 row_mask:0xf bank_mask:0xf
	v_fmac_f32_dpp v49, v209, v37 row_ror:1 row_mask:0xf bank_mask:0xf
	v_rcp_f32_e32 v53, v53
	v_fmac_f32_dpp v50, v210, v38 row_ror:1 row_mask:0xf bank_mask:0xf
	v_fmac_f32_dpp v51, v211, v39 row_ror:1 row_mask:0xf bank_mask:0xf
	v_rcp_f32_e32 v54, v54
	v_fmac_f32_dpp v48, v208, v40 row_ror:2 row_mask:0xf bank_mask:0xf
	v_fmac_f32_dpp v49, v209, v41 row_ror:2 row_mask:0xf bank_mask:0xf
	v_rcp_f32_e32 v55, v55
	v_fmac_f32_dpp v50, v210, v42 row_ror:2 row_mask:0xf bank_mask:0xf
	v_fmac_f32_dpp v51, v211, v43 row_ror:2 row_mask:0xf bank_mask:0xf
	v_pk_mul_f32 v[44:45], v[44:45], v[52:53]
	v_pk_mul_f32 v[46:47], v[46:47], v[54:55]
	v_pk_mul_f32 v[44:45], v[48:49], v[44:45]
	v_pk_mul_f32 v[46:47], v[50:51], v[46:47]
	v_cvt_pk_bf16_f32 v164, v44, v45
	v_cvt_pk_bf16_f32 v165, v46, v47
	v_pk_fma_f32 v[44:45], v[112:113], v[88:89], v[120:121]
	v_pk_fma_f32 v[46:47], v[114:115], v[90:91], v[122:123]
	v_pk_fma_f32 v[48:49], v[108:109], v[84:85], v[116:117]
	v_pk_fma_f32 v[50:51], v[110:111], v[86:87], v[118:119]
	v_fmac_f32_dpp v44, v88, v104 row_shr:1 row_mask:0xf bank_mask:0xf
	v_fmac_f32_dpp v45, v89, v105 row_shr:1 row_mask:0xf bank_mask:0xf
	v_fmac_f32_dpp v46, v90, v106 row_shr:1 row_mask:0xf bank_mask:0xf
	v_fmac_f32_dpp v47, v91, v107 row_shr:1 row_mask:0xf bank_mask:0xf
	v_fmac_f32_dpp v44, v88, v100 row_shr:2 row_mask:0xf bank_mask:0xf
	v_fmac_f32_dpp v45, v89, v101 row_shr:2 row_mask:0xf bank_mask:0xf
	v_fmac_f32_dpp v46, v90, v102 row_shr:2 row_mask:0xf bank_mask:0xf
	v_fmac_f32_dpp v47, v91, v103 row_shr:2 row_mask:0xf bank_mask:0xf
	v_fmac_f32_dpp v44, v128, v28 row_ror:1 row_mask:0xf bank_mask:0xf
	v_fmac_f32_dpp v45, v129, v29 row_ror:1 row_mask:0xf bank_mask:0xf
	v_fmac_f32_dpp v46, v130, v30 row_ror:1 row_mask:0xf bank_mask:0xf
	v_fmac_f32_dpp v47, v131, v31 row_ror:1 row_mask:0xf bank_mask:0xf
	v_fmac_f32_dpp v44, v128, v32 row_ror:2 row_mask:0xf bank_mask:0xf
	v_fmac_f32_dpp v45, v129, v33 row_ror:2 row_mask:0xf bank_mask:0xf
	v_fmac_f32_dpp v46, v130, v34 row_ror:2 row_mask:0xf bank_mask:0xf
	v_fmac_f32_dpp v47, v131, v35 row_ror:2 row_mask:0xf bank_mask:0xf
	v_pk_mul_f32 v[52:53], v[44:45], v[240:241] op_sel_hi:[1,0]
	v_pk_mul_f32 v[54:55], v[46:47], v[240:241] op_sel_hi:[1,0]
	v_exp_f32_e32 v52, v52
	v_fmac_f32_dpp v48, v84, v96 row_shr:1 row_mask:0xf bank_mask:0xf
	v_fmac_f32_dpp v49, v85, v97 row_shr:1 row_mask:0xf bank_mask:0xf
	v_exp_f32_e32 v53, v53
	v_fmac_f32_dpp v50, v86, v98 row_shr:1 row_mask:0xf bank_mask:0xf
	v_fmac_f32_dpp v51, v87, v99 row_shr:1 row_mask:0xf bank_mask:0xf
	v_exp_f32_e32 v54, v54
	v_fmac_f32_dpp v48, v84, v92 row_shr:2 row_mask:0xf bank_mask:0xf
	v_fmac_f32_dpp v49, v85, v93 row_shr:2 row_mask:0xf bank_mask:0xf
	v_exp_f32_e32 v55, v55
	v_fmac_f32_dpp v50, v86, v94 row_shr:2 row_mask:0xf bank_mask:0xf
	v_fmac_f32_dpp v51, v87, v95 row_shr:2 row_mask:0xf bank_mask:0xf
	v_pk_add_f32 v[52:53], v[52:53], v[240:241] op_sel:[0,1] op_sel_hi:[1,1]
	v_pk_add_f32 v[54:55], v[54:55], v[240:241] op_sel:[0,1] op_sel_hi:[1,1]
	v_rcp_f32_e32 v52, v52
	v_fmac_f32_dpp v48, v124, v36 row_ror:1 row_mask:0xf bank_mask:0xf
	v_fmac_f32_dpp v49, v125, v37 row_ror:1 row_mask:0xf bank_mask:0xf
	v_rcp_f32_e32 v53, v53
	v_fmac_f32_dpp v50, v126, v38 row_ror:1 row_mask:0xf bank_mask:0xf
	v_fmac_f32_dpp v51, v127, v39 row_ror:1 row_mask:0xf bank_mask:0xf
	v_rcp_f32_e32 v54, v54
	v_fmac_f32_dpp v48, v124, v40 row_ror:2 row_mask:0xf bank_mask:0xf
	v_fmac_f32_dpp v49, v125, v41 row_ror:2 row_mask:0xf bank_mask:0xf
	v_rcp_f32_e32 v55, v55
	v_fmac_f32_dpp v50, v126, v42 row_ror:2 row_mask:0xf bank_mask:0xf
	v_fmac_f32_dpp v51, v127, v43 row_ror:2 row_mask:0xf bank_mask:0xf
	v_pk_mul_f32 v[44:45], v[44:45], v[52:53]
	v_pk_mul_f32 v[46:47], v[46:47], v[54:55]
	v_pk_mul_f32 v[44:45], v[48:49], v[44:45]
	v_pk_mul_f32 v[46:47], v[50:51], v[46:47]
	v_cvt_pk_bf16_f32 v166, v44, v45
	v_cvt_pk_bf16_f32 v167, v46, v47
	v_pk_fma_f32 v[44:45], v[112:113], v[80:81], v[120:121]
	v_pk_fma_f32 v[46:47], v[114:115], v[82:83], v[122:123]
	v_pk_fma_f32 v[48:49], v[108:109], v[76:77], v[116:117]
	v_pk_fma_f32 v[50:51], v[110:111], v[78:79], v[118:119]
	v_fmac_f32_dpp v44, v80, v104 row_shr:1 row_mask:0xf bank_mask:0xf
	v_fmac_f32_dpp v45, v81, v105 row_shr:1 row_mask:0xf bank_mask:0xf
	v_fmac_f32_dpp v46, v82, v106 row_shr:1 row_mask:0xf bank_mask:0xf
	v_fmac_f32_dpp v47, v83, v107 row_shr:1 row_mask:0xf bank_mask:0xf
	v_fmac_f32_dpp v44, v80, v100 row_shr:2 row_mask:0xf bank_mask:0xf
	v_fmac_f32_dpp v45, v81, v101 row_shr:2 row_mask:0xf bank_mask:0xf
	v_fmac_f32_dpp v46, v82, v102 row_shr:2 row_mask:0xf bank_mask:0xf
	v_fmac_f32_dpp v47, v83, v103 row_shr:2 row_mask:0xf bank_mask:0xf
	v_fmac_f32_dpp v44, v88, v28 row_ror:1 row_mask:0xf bank_mask:0xf
	v_fmac_f32_dpp v45, v89, v29 row_ror:1 row_mask:0xf bank_mask:0xf
	v_fmac_f32_dpp v46, v90, v30 row_ror:1 row_mask:0xf bank_mask:0xf
	v_fmac_f32_dpp v47, v91, v31 row_ror:1 row_mask:0xf bank_mask:0xf
	v_fmac_f32_dpp v44, v88, v32 row_ror:2 row_mask:0xf bank_mask:0xf
	v_fmac_f32_dpp v45, v89, v33 row_ror:2 row_mask:0xf bank_mask:0xf
	v_fmac_f32_dpp v46, v90, v34 row_ror:2 row_mask:0xf bank_mask:0xf
	v_fmac_f32_dpp v47, v91, v35 row_ror:2 row_mask:0xf bank_mask:0xf
	v_pk_mul_f32 v[52:53], v[44:45], v[240:241] op_sel_hi:[1,0]
	v_pk_mul_f32 v[54:55], v[46:47], v[240:241] op_sel_hi:[1,0]
	v_exp_f32_e32 v52, v52
	v_fmac_f32_dpp v48, v76, v96 row_shr:1 row_mask:0xf bank_mask:0xf
	v_fmac_f32_dpp v49, v77, v97 row_shr:1 row_mask:0xf bank_mask:0xf
	v_exp_f32_e32 v53, v53
	v_fmac_f32_dpp v50, v78, v98 row_shr:1 row_mask:0xf bank_mask:0xf
	v_fmac_f32_dpp v51, v79, v99 row_shr:1 row_mask:0xf bank_mask:0xf
	v_exp_f32_e32 v54, v54
	v_fmac_f32_dpp v48, v76, v92 row_shr:2 row_mask:0xf bank_mask:0xf
	v_fmac_f32_dpp v49, v77, v93 row_shr:2 row_mask:0xf bank_mask:0xf
	v_exp_f32_e32 v55, v55
	v_fmac_f32_dpp v50, v78, v94 row_shr:2 row_mask:0xf bank_mask:0xf
	v_fmac_f32_dpp v51, v79, v95 row_shr:2 row_mask:0xf bank_mask:0xf
	v_pk_add_f32 v[52:53], v[52:53], v[240:241] op_sel:[0,1] op_sel_hi:[1,1]
	v_pk_add_f32 v[54:55], v[54:55], v[240:241] op_sel:[0,1] op_sel_hi:[1,1]
	v_rcp_f32_e32 v52, v52
	v_fmac_f32_dpp v48, v84, v36 row_ror:1 row_mask:0xf bank_mask:0xf
	v_fmac_f32_dpp v49, v85, v37 row_ror:1 row_mask:0xf bank_mask:0xf
	v_rcp_f32_e32 v53, v53
	v_fmac_f32_dpp v50, v86, v38 row_ror:1 row_mask:0xf bank_mask:0xf
	v_fmac_f32_dpp v51, v87, v39 row_ror:1 row_mask:0xf bank_mask:0xf
	v_rcp_f32_e32 v54, v54
	v_fmac_f32_dpp v48, v84, v40 row_ror:2 row_mask:0xf bank_mask:0xf
	v_fmac_f32_dpp v49, v85, v41 row_ror:2 row_mask:0xf bank_mask:0xf
	v_rcp_f32_e32 v55, v55
	v_fmac_f32_dpp v50, v86, v42 row_ror:2 row_mask:0xf bank_mask:0xf
	v_fmac_f32_dpp v51, v87, v43 row_ror:2 row_mask:0xf bank_mask:0xf
	v_pk_mul_f32 v[44:45], v[44:45], v[52:53]
	v_pk_mul_f32 v[46:47], v[46:47], v[54:55]
	v_pk_mul_f32 v[44:45], v[48:49], v[44:45]
	v_pk_mul_f32 v[46:47], v[50:51], v[46:47]
	v_cvt_pk_bf16_f32 v128, v44, v45
	v_cvt_pk_bf16_f32 v129, v46, v47
	v_pk_fma_f32 v[44:45], v[112:113], v[72:73], v[120:121]
	v_pk_fma_f32 v[46:47], v[114:115], v[74:75], v[122:123]
	v_pk_fma_f32 v[48:49], v[108:109], v[68:69], v[116:117]
	v_pk_fma_f32 v[50:51], v[110:111], v[70:71], v[118:119]
	v_fmac_f32_dpp v44, v72, v104 row_shr:1 row_mask:0xf bank_mask:0xf
	v_fmac_f32_dpp v45, v73, v105 row_shr:1 row_mask:0xf bank_mask:0xf
	v_fmac_f32_dpp v46, v74, v106 row_shr:1 row_mask:0xf bank_mask:0xf
	v_fmac_f32_dpp v47, v75, v107 row_shr:1 row_mask:0xf bank_mask:0xf
	v_fmac_f32_dpp v44, v72, v100 row_shr:2 row_mask:0xf bank_mask:0xf
	v_fmac_f32_dpp v45, v73, v101 row_shr:2 row_mask:0xf bank_mask:0xf
	v_fmac_f32_dpp v46, v74, v102 row_shr:2 row_mask:0xf bank_mask:0xf
	v_fmac_f32_dpp v47, v75, v103 row_shr:2 row_mask:0xf bank_mask:0xf
	v_fmac_f32_dpp v44, v80, v28 row_ror:1 row_mask:0xf bank_mask:0xf
	v_fmac_f32_dpp v45, v81, v29 row_ror:1 row_mask:0xf bank_mask:0xf
	v_fmac_f32_dpp v46, v82, v30 row_ror:1 row_mask:0xf bank_mask:0xf
	v_fmac_f32_dpp v47, v83, v31 row_ror:1 row_mask:0xf bank_mask:0xf
	v_fmac_f32_dpp v44, v80, v32 row_ror:2 row_mask:0xf bank_mask:0xf
	v_fmac_f32_dpp v45, v81, v33 row_ror:2 row_mask:0xf bank_mask:0xf
	v_fmac_f32_dpp v46, v82, v34 row_ror:2 row_mask:0xf bank_mask:0xf
	v_fmac_f32_dpp v47, v83, v35 row_ror:2 row_mask:0xf bank_mask:0xf
	v_pk_mul_f32 v[52:53], v[44:45], v[240:241] op_sel_hi:[1,0]
	v_pk_mul_f32 v[54:55], v[46:47], v[240:241] op_sel_hi:[1,0]
	v_exp_f32_e32 v52, v52
	v_fmac_f32_dpp v48, v68, v96 row_shr:1 row_mask:0xf bank_mask:0xf
	v_fmac_f32_dpp v49, v69, v97 row_shr:1 row_mask:0xf bank_mask:0xf
	v_exp_f32_e32 v53, v53
	v_fmac_f32_dpp v50, v70, v98 row_shr:1 row_mask:0xf bank_mask:0xf
	v_fmac_f32_dpp v51, v71, v99 row_shr:1 row_mask:0xf bank_mask:0xf
	v_exp_f32_e32 v54, v54
	v_fmac_f32_dpp v48, v68, v92 row_shr:2 row_mask:0xf bank_mask:0xf
	v_fmac_f32_dpp v49, v69, v93 row_shr:2 row_mask:0xf bank_mask:0xf
	v_exp_f32_e32 v55, v55
	v_fmac_f32_dpp v50, v70, v94 row_shr:2 row_mask:0xf bank_mask:0xf
	v_fmac_f32_dpp v51, v71, v95 row_shr:2 row_mask:0xf bank_mask:0xf
	v_pk_add_f32 v[52:53], v[52:53], v[240:241] op_sel:[0,1] op_sel_hi:[1,1]
	v_pk_add_f32 v[54:55], v[54:55], v[240:241] op_sel:[0,1] op_sel_hi:[1,1]
	v_rcp_f32_e32 v52, v52
	v_fmac_f32_dpp v48, v76, v36 row_ror:1 row_mask:0xf bank_mask:0xf
	v_fmac_f32_dpp v49, v77, v37 row_ror:1 row_mask:0xf bank_mask:0xf
	v_rcp_f32_e32 v53, v53
	v_fmac_f32_dpp v50, v78, v38 row_ror:1 row_mask:0xf bank_mask:0xf
	v_fmac_f32_dpp v51, v79, v39 row_ror:1 row_mask:0xf bank_mask:0xf
	v_rcp_f32_e32 v54, v54
	v_fmac_f32_dpp v48, v76, v40 row_ror:2 row_mask:0xf bank_mask:0xf
	v_fmac_f32_dpp v49, v77, v41 row_ror:2 row_mask:0xf bank_mask:0xf
	v_rcp_f32_e32 v55, v55
	v_fmac_f32_dpp v50, v78, v42 row_ror:2 row_mask:0xf bank_mask:0xf
	v_fmac_f32_dpp v51, v79, v43 row_ror:2 row_mask:0xf bank_mask:0xf
	v_pk_mul_f32 v[44:45], v[44:45], v[52:53]
	v_pk_mul_f32 v[46:47], v[46:47], v[54:55]
	v_pk_mul_f32 v[44:45], v[48:49], v[44:45]
	v_pk_mul_f32 v[46:47], v[50:51], v[46:47]
	v_cvt_pk_bf16_f32 v130, v44, v45
	v_cvt_pk_bf16_f32 v131, v46, v47
	s_cmp_eq_u32 s63, 0
	s_cbranch_scc1 .Leu_halo_skip_a1n0
	v_subrev_u32_e32 v58, 12, v56
	v_mul_u32_u24_e32 v58, 0xb000, v58
	v_lshl_add_u32 v58, v57, 5, v58
	s_mul_i32 s39, s12, 0x2c000
	s_lshl_b32 s40, s13, 9
	s_add_i32 s39, s39, s40
	s_lshl_b32 s40, s64, 2
	s_add_i32 s39, s39, s40
	s_add_u32 s20, s72, s39
	s_addc_u32 s21, s73, 0
	s_add_u32 s22, s20, 0x5800
	s_addc_u32 s23, s21, 0
	s_and_saveexec_b64 s[8:9], s[10:11]
	global_store_dwordx4 v58, v[72:75], s[20:21]
	global_store_dwordx4 v58, v[68:71], s[22:23]
	s_and_b32 s39, s12, 7
	s_cmp_lg_u32 s39, 7
	s_cbranch_scc1 .Leu_ffn_skip_a1n0
	v_subrev_u32_e32 v59, 14, v56
	v_mul_u32_u24_e32 v59, 0xb000, v59
	v_lshl_add_u32 v59, v57, 5, v59
	s_lshr_b32 s39, s12, 3
	s_mul_i32 s39, s39, 0x16000
	s_lshl_b32 s40, s13, 9
	s_add_i32 s39, s39, s40
	s_lshl_b32 s40, s64, 2
	s_add_i32 s39, s39, s40
	s_add_u32 s20, s28, s39
	s_addc_u32 s21, s29, 0
	s_add_u32 s22, s20, 0x5800
	s_addc_u32 s23, s21, 0
	global_store_dwordx4 v59, v[72:75], s[20:21]
	global_store_dwordx4 v59, v[68:71], s[22:23]

.Leu_pv0_skip_n1:
	s_cmp_eq_u32 s63, 0
	s_movk_i32 s40, 0x1000
	s_cselect_b32 s39, 0x800, s40
	s_add_i32 s39, s39, s67
	v_add_u32_e32 v59, s39, v217
	s_and_saveexec_b64 s[8:9], s[10:11]
	ds_read_b128 v[204:207], v59 offset:16
	ds_read_b128 v[208:211], v59 offset:144
	s_mov_b64 exec, s[8:9]
	s_waitcnt vmcnt(0) lgkmcnt(0)
	v_mul_f32_e32 v28, v192, v250
	v_mul_f32_e32 v29, v193, v250
	v_mul_f32_e32 v30, v194, v250
	v_mul_f32_e32 v31, v195, v250
	v_mul_f32_e32 v32, v236, v251
	v_mul_f32_e32 v33, v237, v251
	v_mul_f32_e32 v34, v238, v251
	v_mul_f32_e32 v35, v239, v251
	v_mul_f32_e32 v36, v176, v250
	v_mul_f32_e32 v37, v177, v250
	v_mul_f32_e32 v38, v178, v250
	v_mul_f32_e32 v39, v179, v250
	v_mul_f32_e32 v40, v184, v251
	v_mul_f32_e32 v41, v185, v251
	v_mul_f32_e32 v42, v186, v251
	v_mul_f32_e32 v43, v187, v251
	v_pk_fma_f32 v[44:45], v[180:181], v[160:161], v[188:189]
	v_pk_fma_f32 v[46:47], v[182:183], v[162:163], v[190:191]
	v_pk_fma_f32 v[48:49], v[172:173], v[156:157], v[168:169]
	v_pk_fma_f32 v[50:51], v[174:175], v[158:159], v[170:171]
	v_fmac_f32_dpp v44, v160, v192 row_shr:1 row_mask:0xf bank_mask:0xf
	v_fmac_f32_dpp v45, v161, v193 row_shr:1 row_mask:0xf bank_mask:0xf
	v_fmac_f32_dpp v46, v162, v194 row_shr:1 row_mask:0xf bank_mask:0xf
	v_fmac_f32_dpp v47, v163, v195 row_shr:1 row_mask:0xf bank_mask:0xf
	v_fmac_f32_dpp v44, v160, v236 row_shr:2 row_mask:0xf bank_mask:0xf
	v_fmac_f32_dpp v45, v161, v237 row_shr:2 row_mask:0xf bank_mask:0xf
	v_fmac_f32_dpp v46, v162, v238 row_shr:2 row_mask:0xf bank_mask:0xf
	v_fmac_f32_dpp v47, v163, v239 row_shr:2 row_mask:0xf bank_mask:0xf
	v_fmac_f32_dpp v44, v196, v28 row_ror:1 row_mask:0xf bank_mask:0xf
	v_fmac_f32_dpp v45, v197, v29 row_ror:1 row_mask:0xf bank_mask:0xf
	v_fmac_f32_dpp v46, v198, v30 row_ror:1 row_mask:0xf bank_mask:0xf
	v_fmac_f32_dpp v47, v199, v31 row_ror:1 row_mask:0xf bank_mask:0xf
	v_fmac_f32_dpp v44, v196, v32 row_ror:2 row_mask:0xf bank_mask:0xf
	v_fmac_f32_dpp v45, v197, v33 row_ror:2 row_mask:0xf bank_mask:0xf
	v_fmac_f32_dpp v46, v198, v34 row_ror:2 row_mask:0xf bank_mask:0xf
	v_fmac_f32_dpp v47, v199, v35 row_ror:2 row_mask:0xf bank_mask:0xf
	v_pk_mul_f32 v[52:53], v[44:45], v[240:241] op_sel_hi:[1,0]
	v_pk_mul_f32 v[54:55], v[46:47], v[240:241] op_sel_hi:[1,0]
	v_exp_f32_e32 v52, v52
	v_fmac_f32_dpp v48, v156, v176 row_shr:1 row_mask:0xf bank_mask:0xf
	v_fmac_f32_dpp v49, v157, v177 row_shr:1 row_mask:0xf bank_mask:0xf
	v_exp_f32_e32 v53, v53
	v_fmac_f32_dpp v50, v158, v178 row_shr:1 row_mask:0xf bank_mask:0xf
	v_fmac_f32_dpp v51, v159, v179 row_shr:1 row_mask:0xf bank_mask:0xf
	v_exp_f32_e32 v54, v54
	v_fmac_f32_dpp v48, v156, v184 row_shr:2 row_mask:0xf bank_mask:0xf
	v_fmac_f32_dpp v49, v157, v185 row_shr:2 row_mask:0xf bank_mask:0xf
	v_exp_f32_e32 v55, v55
	v_fmac_f32_dpp v50, v158, v186 row_shr:2 row_mask:0xf bank_mask:0xf
	v_fmac_f32_dpp v51, v159, v187 row_shr:2 row_mask:0xf bank_mask:0xf
	v_pk_add_f32 v[52:53], v[52:53], v[240:241] op_sel:[0,1] op_sel_hi:[1,1]
	v_pk_add_f32 v[54:55], v[54:55], v[240:241] op_sel:[0,1] op_sel_hi:[1,1]
	v_rcp_f32_e32 v52, v52
	v_fmac_f32_dpp v48, v200, v36 row_ror:1 row_mask:0xf bank_mask:0xf
	v_fmac_f32_dpp v49, v201, v37 row_ror:1 row_mask:0xf bank_mask:0xf
	v_rcp_f32_e32 v53, v53
	v_fmac_f32_dpp v50, v202, v38 row_ror:1 row_mask:0xf bank_mask:0xf
	v_fmac_f32_dpp v51, v203, v39 row_ror:1 row_mask:0xf bank_mask:0xf
	v_rcp_f32_e32 v54, v54
	v_fmac_f32_dpp v48, v200, v40 row_ror:2 row_mask:0xf bank_mask:0xf
	v_fmac_f32_dpp v49, v201, v41 row_ror:2 row_mask:0xf bank_mask:0xf
	v_rcp_f32_e32 v55, v55
	v_fmac_f32_dpp v50, v202, v42 row_ror:2 row_mask:0xf bank_mask:0xf
	v_fmac_f32_dpp v51, v203, v43 row_ror:2 row_mask:0xf bank_mask:0xf
	v_pk_mul_f32 v[44:45], v[44:45], v[52:53]
	v_pk_mul_f32 v[46:47], v[46:47], v[54:55]
	v_pk_mul_f32 v[44:45], v[48:49], v[44:45]
	v_pk_mul_f32 v[46:47], v[50:51], v[46:47]
	v_mov_b32_e32 v124, v242
	v_mov_b32_e32 v125, v243
	v_cvt_pk_bf16_f32 v126, v44, v45
	v_cvt_pk_bf16_f32 v127, v46, v47
	v_mov_b32_e32 v58, v234
	s_mov_b64 s[8:9], exec
	s_and_b32 s39, s12, 7
	s_cmp_eq_u32 s39, 0
	s_cbranch_scc1 .Leu_g00_all
	s_cmp_lg_u32 s63, 0
	s_cbranch_scc1 .Leu_g00_all
	s_andn2_b64 exec, exec, s[14:15]

.Leu_halo_skip_a0n1:
	v_pk_fma_f32 v[44:45], v[180:181], v[152:153], v[188:189]
	v_pk_fma_f32 v[46:47], v[182:183], v[154:155], v[190:191]
	v_pk_fma_f32 v[48:49], v[172:173], v[148:149], v[168:169]
	v_pk_fma_f32 v[50:51], v[174:175], v[150:151], v[170:171]
	v_fmac_f32_dpp v44, v152, v192 row_shr:1 row_mask:0xf bank_mask:0xf
	v_fmac_f32_dpp v45, v153, v193 row_shr:1 row_mask:0xf bank_mask:0xf
	v_fmac_f32_dpp v46, v154, v194 row_shr:1 row_mask:0xf bank_mask:0xf
	v_fmac_f32_dpp v47, v155, v195 row_shr:1 row_mask:0xf bank_mask:0xf
	v_fmac_f32_dpp v44, v152, v236 row_shr:2 row_mask:0xf bank_mask:0xf
	v_fmac_f32_dpp v45, v153, v237 row_shr:2 row_mask:0xf bank_mask:0xf
	v_fmac_f32_dpp v46, v154, v238 row_shr:2 row_mask:0xf bank_mask:0xf
	v_fmac_f32_dpp v47, v155, v239 row_shr:2 row_mask:0xf bank_mask:0xf
	v_fmac_f32_dpp v44, v160, v28 row_ror:1 row_mask:0xf bank_mask:0xf
	v_fmac_f32_dpp v45, v161, v29 row_ror:1 row_mask:0xf bank_mask:0xf
	v_fmac_f32_dpp v46, v162, v30 row_ror:1 row_mask:0xf bank_mask:0xf
	v_fmac_f32_dpp v47, v163, v31 row_ror:1 row_mask:0xf bank_mask:0xf
	v_fmac_f32_dpp v44, v160, v32 row_ror:2 row_mask:0xf bank_mask:0xf
	v_fmac_f32_dpp v45, v161, v33 row_ror:2 row_mask:0xf bank_mask:0xf
	v_fmac_f32_dpp v46, v162, v34 row_ror:2 row_mask:0xf bank_mask:0xf
	v_fmac_f32_dpp v47, v163, v35 row_ror:2 row_mask:0xf bank_mask:0xf
	v_pk_mul_f32 v[52:53], v[44:45], v[240:241] op_sel_hi:[1,0]
	v_pk_mul_f32 v[54:55], v[46:47], v[240:241] op_sel_hi:[1,0]
	v_exp_f32_e32 v52, v52
	v_fmac_f32_dpp v48, v148, v176 row_shr:1 row_mask:0xf bank_mask:0xf
	v_fmac_f32_dpp v49, v149, v177 row_shr:1 row_mask:0xf bank_mask:0xf
	v_exp_f32_e32 v53, v53
	v_fmac_f32_dpp v50, v150, v178 row_shr:1 row_mask:0xf bank_mask:0xf
	v_fmac_f32_dpp v51, v151, v179 row_shr:1 row_mask:0xf bank_mask:0xf
	v_exp_f32_e32 v54, v54
	v_fmac_f32_dpp v48, v148, v184 row_shr:2 row_mask:0xf bank_mask:0xf
	v_fmac_f32_dpp v49, v149, v185 row_shr:2 row_mask:0xf bank_mask:0xf
	v_exp_f32_e32 v55, v55
	v_fmac_f32_dpp v50, v150, v186 row_shr:2 row_mask:0xf bank_mask:0xf
	v_fmac_f32_dpp v51, v151, v187 row_shr:2 row_mask:0xf bank_mask:0xf
	v_pk_add_f32 v[52:53], v[52:53], v[240:241] op_sel:[0,1] op_sel_hi:[1,1]
	v_pk_add_f32 v[54:55], v[54:55], v[240:241] op_sel:[0,1] op_sel_hi:[1,1]
	v_rcp_f32_e32 v52, v52
	v_fmac_f32_dpp v48, v156, v36 row_ror:1 row_mask:0xf bank_mask:0xf
	v_fmac_f32_dpp v49, v157, v37 row_ror:1 row_mask:0xf bank_mask:0xf
	v_rcp_f32_e32 v53, v53
	v_fmac_f32_dpp v50, v158, v38 row_ror:1 row_mask:0xf bank_mask:0xf
	v_fmac_f32_dpp v51, v159, v39 row_ror:1 row_mask:0xf bank_mask:0xf
	v_rcp_f32_e32 v54, v54
	v_fmac_f32_dpp v48, v156, v40 row_ror:2 row_mask:0xf bank_mask:0xf
	v_fmac_f32_dpp v49, v157, v41 row_ror:2 row_mask:0xf bank_mask:0xf
	v_rcp_f32_e32 v55, v55
	v_fmac_f32_dpp v50, v158, v42 row_ror:2 row_mask:0xf bank_mask:0xf
	v_fmac_f32_dpp v51, v159, v43 row_ror:2 row_mask:0xf bank_mask:0xf
	v_pk_mul_f32 v[44:45], v[44:45], v[52:53]
	v_pk_mul_f32 v[46:47], v[46:47], v[54:55]
	v_pk_mul_f32 v[44:45], v[48:49], v[44:45]
	v_pk_mul_f32 v[46:47], v[50:51], v[46:47]
	v_mov_b32_e32 v88, v244
	v_mov_b32_e32 v89, v245
	v_cvt_pk_bf16_f32 v90, v44, v45
	v_cvt_pk_bf16_f32 v91, v46, v47
	v_add_u32_e32 v58, 0x2c000, v234
	global_store_dwordx4 v58, v[88:91], s[16:17]
	v_pk_fma_f32 v[44:45], v[180:181], v[144:145], v[188:189]
	v_pk_fma_f32 v[46:47], v[182:183], v[146:147], v[190:191]
	v_pk_fma_f32 v[48:49], v[172:173], v[140:141], v[168:169]
	v_pk_fma_f32 v[50:51], v[174:175], v[142:143], v[170:171]
	v_fmac_f32_dpp v44, v144, v192 row_shr:1 row_mask:0xf bank_mask:0xf
	v_fmac_f32_dpp v45, v145, v193 row_shr:1 row_mask:0xf bank_mask:0xf
	v_fmac_f32_dpp v46, v146, v194 row_shr:1 row_mask:0xf bank_mask:0xf
	v_fmac_f32_dpp v47, v147, v195 row_shr:1 row_mask:0xf bank_mask:0xf
	v_fmac_f32_dpp v44, v144, v236 row_shr:2 row_mask:0xf bank_mask:0xf
	v_fmac_f32_dpp v45, v145, v237 row_shr:2 row_mask:0xf bank_mask:0xf
	v_fmac_f32_dpp v46, v146, v238 row_shr:2 row_mask:0xf bank_mask:0xf
	v_fmac_f32_dpp v47, v147, v239 row_shr:2 row_mask:0xf bank_mask:0xf
	v_fmac_f32_dpp v44, v152, v28 row_ror:1 row_mask:0xf bank_mask:0xf
	v_fmac_f32_dpp v45, v153, v29 row_ror:1 row_mask:0xf bank_mask:0xf
	v_fmac_f32_dpp v46, v154, v30 row_ror:1 row_mask:0xf bank_mask:0xf
	v_fmac_f32_dpp v47, v155, v31 row_ror:1 row_mask:0xf bank_mask:0xf
	v_fmac_f32_dpp v44, v152, v32 row_ror:2 row_mask:0xf bank_mask:0xf
	v_fmac_f32_dpp v45, v153, v33 row_ror:2 row_mask:0xf bank_mask:0xf
	v_fmac_f32_dpp v46, v154, v34 row_ror:2 row_mask:0xf bank_mask:0xf
	v_fmac_f32_dpp v47, v155, v35 row_ror:2 row_mask:0xf bank_mask:0xf
	v_pk_mul_f32 v[52:53], v[44:45], v[240:241] op_sel_hi:[1,0]
	v_pk_mul_f32 v[54:55], v[46:47], v[240:241] op_sel_hi:[1,0]
	v_exp_f32_e32 v52, v52
	v_fmac_f32_dpp v48, v140, v176 row_shr:1 row_mask:0xf bank_mask:0xf
	v_fmac_f32_dpp v49, v141, v177 row_shr:1 row_mask:0xf bank_mask:0xf
	v_exp_f32_e32 v53, v53
	v_fmac_f32_dpp v50, v142, v178 row_shr:1 row_mask:0xf bank_mask:0xf
	v_fmac_f32_dpp v51, v143, v179 row_shr:1 row_mask:0xf bank_mask:0xf
	v_exp_f32_e32 v54, v54
	v_fmac_f32_dpp v48, v140, v184 row_shr:2 row_mask:0xf bank_mask:0xf
	v_fmac_f32_dpp v49, v141, v185 row_shr:2 row_mask:0xf bank_mask:0xf
	v_exp_f32_e32 v55, v55
	v_fmac_f32_dpp v50, v142, v186 row_shr:2 row_mask:0xf bank_mask:0xf
	v_fmac_f32_dpp v51, v143, v187 row_shr:2 row_mask:0xf bank_mask:0xf
	v_pk_add_f32 v[52:53], v[52:53], v[240:241] op_sel:[0,1] op_sel_hi:[1,1]
	v_pk_add_f32 v[54:55], v[54:55], v[240:241] op_sel:[0,1] op_sel_hi:[1,1]
	v_rcp_f32_e32 v52, v52
	v_fmac_f32_dpp v48, v148, v36 row_ror:1 row_mask:0xf bank_mask:0xf
	v_fmac_f32_dpp v49, v149, v37 row_ror:1 row_mask:0xf bank_mask:0xf
	v_rcp_f32_e32 v53, v53
	v_fmac_f32_dpp v50, v150, v38 row_ror:1 row_mask:0xf bank_mask:0xf
	v_fmac_f32_dpp v51, v151, v39 row_ror:1 row_mask:0xf bank_mask:0xf
	v_rcp_f32_e32 v54, v54
	v_fmac_f32_dpp v48, v148, v40 row_ror:2 row_mask:0xf bank_mask:0xf
	v_fmac_f32_dpp v49, v149, v41 row_ror:2 row_mask:0xf bank_mask:0xf
	v_rcp_f32_e32 v55, v55
	v_fmac_f32_dpp v50, v150, v42 row_ror:2 row_mask:0xf bank_mask:0xf
	v_fmac_f32_dpp v51, v151, v43 row_ror:2 row_mask:0xf bank_mask:0xf
	v_pk_mul_f32 v[44:45], v[44:45], v[52:53]
	v_pk_mul_f32 v[46:47], v[46:47], v[54:55]
	v_pk_mul_f32 v[44:45], v[48:49], v[44:45]
	v_pk_mul_f32 v[46:47], v[50:51], v[46:47]
	v_mov_b32_e32 v124, v246
	v_mov_b32_e32 v125, v247
	v_cvt_pk_bf16_f32 v126, v44, v45
	v_cvt_pk_bf16_f32 v127, v46, v47
	v_add_u32_e32 v58, 0x58000, v234
	global_store_dwordx4 v58, v[124:127], s[16:17]
	v_pk_fma_f32 v[44:45], v[180:181], v[136:137], v[188:189]
	v_pk_fma_f32 v[46:47], v[182:183], v[138:139], v[190:191]
	v_pk_fma_f32 v[48:49], v[172:173], v[132:133], v[168:169]
	v_pk_fma_f32 v[50:51], v[174:175], v[134:135], v[170:171]
	v_fmac_f32_dpp v44, v136, v192 row_shr:1 row_mask:0xf bank_mask:0xf
	v_fmac_f32_dpp v45, v137, v193 row_shr:1 row_mask:0xf bank_mask:0xf
	v_fmac_f32_dpp v46, v138, v194 row_shr:1 row_mask:0xf bank_mask:0xf
	v_fmac_f32_dpp v47, v139, v195 row_shr:1 row_mask:0xf bank_mask:0xf
	v_fmac_f32_dpp v44, v136, v236 row_shr:2 row_mask:0xf bank_mask:0xf
	v_fmac_f32_dpp v45, v137, v237 row_shr:2 row_mask:0xf bank_mask:0xf
	v_fmac_f32_dpp v46, v138, v238 row_shr:2 row_mask:0xf bank_mask:0xf
	v_fmac_f32_dpp v47, v139, v239 row_shr:2 row_mask:0xf bank_mask:0xf
	v_fmac_f32_dpp v44, v144, v28 row_ror:1 row_mask:0xf bank_mask:0xf
	v_fmac_f32_dpp v45, v145, v29 row_ror:1 row_mask:0xf bank_mask:0xf
	v_fmac_f32_dpp v46, v146, v30 row_ror:1 row_mask:0xf bank_mask:0xf
	v_fmac_f32_dpp v47, v147, v31 row_ror:1 row_mask:0xf bank_mask:0xf
	v_fmac_f32_dpp v44, v144, v32 row_ror:2 row_mask:0xf bank_mask:0xf
	v_fmac_f32_dpp v45, v145, v33 row_ror:2 row_mask:0xf bank_mask:0xf
	v_fmac_f32_dpp v46, v146, v34 row_ror:2 row_mask:0xf bank_mask:0xf
	v_fmac_f32_dpp v47, v147, v35 row_ror:2 row_mask:0xf bank_mask:0xf
	v_pk_mul_f32 v[52:53], v[44:45], v[240:241] op_sel_hi:[1,0]
	v_pk_mul_f32 v[54:55], v[46:47], v[240:241] op_sel_hi:[1,0]
	v_exp_f32_e32 v52, v52
	v_fmac_f32_dpp v48, v132, v176 row_shr:1 row_mask:0xf bank_mask:0xf
	v_fmac_f32_dpp v49, v133, v177 row_shr:1 row_mask:0xf bank_mask:0xf
	v_exp_f32_e32 v53, v53
	v_fmac_f32_dpp v50, v134, v178 row_shr:1 row_mask:0xf bank_mask:0xf
	v_fmac_f32_dpp v51, v135, v179 row_shr:1 row_mask:0xf bank_mask:0xf
	v_exp_f32_e32 v54, v54
	v_fmac_f32_dpp v48, v132, v184 row_shr:2 row_mask:0xf bank_mask:0xf
	v_fmac_f32_dpp v49, v133, v185 row_shr:2 row_mask:0xf bank_mask:0xf
	v_exp_f32_e32 v55, v55
	v_fmac_f32_dpp v50, v134, v186 row_shr:2 row_mask:0xf bank_mask:0xf
	v_fmac_f32_dpp v51, v135, v187 row_shr:2 row_mask:0xf bank_mask:0xf
	v_pk_add_f32 v[52:53], v[52:53], v[240:241] op_sel:[0,1] op_sel_hi:[1,1]
	v_pk_add_f32 v[54:55], v[54:55], v[240:241] op_sel:[0,1] op_sel_hi:[1,1]
	v_rcp_f32_e32 v52, v52
	v_fmac_f32_dpp v48, v140, v36 row_ror:1 row_mask:0xf bank_mask:0xf
	v_fmac_f32_dpp v49, v141, v37 row_ror:1 row_mask:0xf bank_mask:0xf
	v_rcp_f32_e32 v53, v53
	v_fmac_f32_dpp v50, v142, v38 row_ror:1 row_mask:0xf bank_mask:0xf
	v_fmac_f32_dpp v51, v143, v39 row_ror:1 row_mask:0xf bank_mask:0xf
	v_rcp_f32_e32 v54, v54
	v_fmac_f32_dpp v48, v140, v40 row_ror:2 row_mask:0xf bank_mask:0xf
	v_fmac_f32_dpp v49, v141, v41 row_ror:2 row_mask:0xf bank_mask:0xf
	v_rcp_f32_e32 v55, v55
	v_fmac_f32_dpp v50, v142, v42 row_ror:2 row_mask:0xf bank_mask:0xf
	v_fmac_f32_dpp v51, v143, v43 row_ror:2 row_mask:0xf bank_mask:0xf
	v_pk_mul_f32 v[44:45], v[44:45], v[52:53]
	v_pk_mul_f32 v[46:47], v[46:47], v[54:55]
	v_pk_mul_f32 v[44:45], v[48:49], v[44:45]
	v_pk_mul_f32 v[46:47], v[50:51], v[46:47]
	v_mov_b32_e32 v88, v248
	v_mov_b32_e32 v89, v249
	v_cvt_pk_bf16_f32 v90, v44, v45
	v_cvt_pk_bf16_f32 v91, v46, v47
	v_add_u32_e32 v58, 0x84000, v234
	global_store_dwordx4 v58, v[88:91], s[16:17]
	v_pk_fma_f32 v[44:45], v[180:181], v[64:65], v[188:189]
	v_pk_fma_f32 v[46:47], v[182:183], v[66:67], v[190:191]
	v_pk_fma_f32 v[48:49], v[172:173], v[60:61], v[168:169]
	v_pk_fma_f32 v[50:51], v[174:175], v[62:63], v[170:171]
	v_fmac_f32_dpp v44, v64, v192 row_shr:1 row_mask:0xf bank_mask:0xf
	v_fmac_f32_dpp v45, v65, v193 row_shr:1 row_mask:0xf bank_mask:0xf
	v_fmac_f32_dpp v46, v66, v194 row_shr:1 row_mask:0xf bank_mask:0xf
	v_fmac_f32_dpp v47, v67, v195 row_shr:1 row_mask:0xf bank_mask:0xf
	v_fmac_f32_dpp v44, v64, v236 row_shr:2 row_mask:0xf bank_mask:0xf
	v_fmac_f32_dpp v45, v65, v237 row_shr:2 row_mask:0xf bank_mask:0xf
	v_fmac_f32_dpp v46, v66, v238 row_shr:2 row_mask:0xf bank_mask:0xf
	v_fmac_f32_dpp v47, v67, v239 row_shr:2 row_mask:0xf bank_mask:0xf
	v_fmac_f32_dpp v44, v204, v28 row_ror:1 row_mask:0xf bank_mask:0xf
	v_fmac_f32_dpp v45, v205, v29 row_ror:1 row_mask:0xf bank_mask:0xf
	v_fmac_f32_dpp v46, v206, v30 row_ror:1 row_mask:0xf bank_mask:0xf
	v_fmac_f32_dpp v47, v207, v31 row_ror:1 row_mask:0xf bank_mask:0xf
	v_fmac_f32_dpp v44, v204, v32 row_ror:2 row_mask:0xf bank_mask:0xf
	v_fmac_f32_dpp v45, v205, v33 row_ror:2 row_mask:0xf bank_mask:0xf
	v_fmac_f32_dpp v46, v206, v34 row_ror:2 row_mask:0xf bank_mask:0xf
	v_fmac_f32_dpp v47, v207, v35 row_ror:2 row_mask:0xf bank_mask:0xf
	v_pk_mul_f32 v[52:53], v[44:45], v[240:241] op_sel_hi:[1,0]
	v_pk_mul_f32 v[54:55], v[46:47], v[240:241] op_sel_hi:[1,0]
	v_exp_f32_e32 v52, v52
	v_fmac_f32_dpp v48, v60, v176 row_shr:1 row_mask:0xf bank_mask:0xf
	v_fmac_f32_dpp v49, v61, v177 row_shr:1 row_mask:0xf bank_mask:0xf
	v_exp_f32_e32 v53, v53
	v_fmac_f32_dpp v50, v62, v178 row_shr:1 row_mask:0xf bank_mask:0xf
	v_fmac_f32_dpp v51, v63, v179 row_shr:1 row_mask:0xf bank_mask:0xf
	v_exp_f32_e32 v54, v54
	v_fmac_f32_dpp v48, v60, v184 row_shr:2 row_mask:0xf bank_mask:0xf
	v_fmac_f32_dpp v49, v61, v185 row_shr:2 row_mask:0xf bank_mask:0xf
	v_exp_f32_e32 v55, v55
	v_fmac_f32_dpp v50, v62, v186 row_shr:2 row_mask:0xf bank_mask:0xf
	v_fmac_f32_dpp v51, v63, v187 row_shr:2 row_mask:0xf bank_mask:0xf
	v_pk_add_f32 v[52:53], v[52:53], v[240:241] op_sel:[0,1] op_sel_hi:[1,1]
	v_pk_add_f32 v[54:55], v[54:55], v[240:241] op_sel:[0,1] op_sel_hi:[1,1]
	v_rcp_f32_e32 v52, v52
	v_fmac_f32_dpp v48, v208, v36 row_ror:1 row_mask:0xf bank_mask:0xf
	v_fmac_f32_dpp v49, v209, v37 row_ror:1 row_mask:0xf bank_mask:0xf
	v_rcp_f32_e32 v53, v53
	v_fmac_f32_dpp v50, v210, v38 row_ror:1 row_mask:0xf bank_mask:0xf
	v_fmac_f32_dpp v51, v211, v39 row_ror:1 row_mask:0xf bank_mask:0xf
	v_rcp_f32_e32 v54, v54
	v_fmac_f32_dpp v48, v208, v40 row_ror:2 row_mask:0xf bank_mask:0xf
	v_fmac_f32_dpp v49, v209, v41 row_ror:2 row_mask:0xf bank_mask:0xf
	v_rcp_f32_e32 v55, v55
	v_fmac_f32_dpp v50, v210, v42 row_ror:2 row_mask:0xf bank_mask:0xf
	v_fmac_f32_dpp v51, v211, v43 row_ror:2 row_mask:0xf bank_mask:0xf
	v_pk_mul_f32 v[44:45], v[44:45], v[52:53]
	v_pk_mul_f32 v[46:47], v[46:47], v[54:55]
	v_pk_mul_f32 v[44:45], v[48:49], v[44:45]
	v_pk_mul_f32 v[46:47], v[50:51], v[46:47]
	v_mov_b32_e32 v124, v164
	v_mov_b32_e32 v125, v165
	v_cvt_pk_bf16_f32 v126, v44, v45
	v_cvt_pk_bf16_f32 v127, v46, v47
	v_mov_b32_e32 v58, v234
	global_store_dwordx4 v58, v[124:127], s[18:19]
	v_pk_fma_f32 v[44:45], v[180:181], v[24:25], v[188:189]
	v_pk_fma_f32 v[46:47], v[182:183], v[26:27], v[190:191]
	v_pk_fma_f32 v[48:49], v[172:173], v[20:21], v[168:169]
	v_pk_fma_f32 v[50:51], v[174:175], v[22:23], v[170:171]
	v_fmac_f32_dpp v44, v24, v192 row_shr:1 row_mask:0xf bank_mask:0xf
	v_fmac_f32_dpp v45, v25, v193 row_shr:1 row_mask:0xf bank_mask:0xf
	v_fmac_f32_dpp v46, v26, v194 row_shr:1 row_mask:0xf bank_mask:0xf
	v_fmac_f32_dpp v47, v27, v195 row_shr:1 row_mask:0xf bank_mask:0xf
	v_fmac_f32_dpp v44, v24, v236 row_shr:2 row_mask:0xf bank_mask:0xf
	v_fmac_f32_dpp v45, v25, v237 row_shr:2 row_mask:0xf bank_mask:0xf
	v_fmac_f32_dpp v46, v26, v238 row_shr:2 row_mask:0xf bank_mask:0xf
	v_fmac_f32_dpp v47, v27, v239 row_shr:2 row_mask:0xf bank_mask:0xf
	v_fmac_f32_dpp v44, v64, v28 row_ror:1 row_mask:0xf bank_mask:0xf
	v_fmac_f32_dpp v45, v65, v29 row_ror:1 row_mask:0xf bank_mask:0xf
	v_fmac_f32_dpp v46, v66, v30 row_ror:1 row_mask:0xf bank_mask:0xf
	v_fmac_f32_dpp v47, v67, v31 row_ror:1 row_mask:0xf bank_mask:0xf
	v_fmac_f32_dpp v44, v64, v32 row_ror:2 row_mask:0xf bank_mask:0xf
	v_fmac_f32_dpp v45, v65, v33 row_ror:2 row_mask:0xf bank_mask:0xf
	v_fmac_f32_dpp v46, v66, v34 row_ror:2 row_mask:0xf bank_mask:0xf
	v_fmac_f32_dpp v47, v67, v35 row_ror:2 row_mask:0xf bank_mask:0xf
	v_pk_mul_f32 v[52:53], v[44:45], v[240:241] op_sel_hi:[1,0]
	v_pk_mul_f32 v[54:55], v[46:47], v[240:241] op_sel_hi:[1,0]
	v_exp_f32_e32 v52, v52
	v_fmac_f32_dpp v48, v20, v176 row_shr:1 row_mask:0xf bank_mask:0xf
	v_fmac_f32_dpp v49, v21, v177 row_shr:1 row_mask:0xf bank_mask:0xf
	v_exp_f32_e32 v53, v53
	v_fmac_f32_dpp v50, v22, v178 row_shr:1 row_mask:0xf bank_mask:0xf
	v_fmac_f32_dpp v51, v23, v179 row_shr:1 row_mask:0xf bank_mask:0xf
	v_exp_f32_e32 v54, v54
	v_fmac_f32_dpp v48, v20, v184 row_shr:2 row_mask:0xf bank_mask:0xf
	v_fmac_f32_dpp v49, v21, v185 row_shr:2 row_mask:0xf bank_mask:0xf
	v_exp_f32_e32 v55, v55
	v_fmac_f32_dpp v50, v22, v186 row_shr:2 row_mask:0xf bank_mask:0xf
	v_fmac_f32_dpp v51, v23, v187 row_shr:2 row_mask:0xf bank_mask:0xf
	v_pk_add_f32 v[52:53], v[52:53], v[240:241] op_sel:[0,1] op_sel_hi:[1,1]
	v_pk_add_f32 v[54:55], v[54:55], v[240:241] op_sel:[0,1] op_sel_hi:[1,1]
	v_rcp_f32_e32 v52, v52
	v_fmac_f32_dpp v48, v60, v36 row_ror:1 row_mask:0xf bank_mask:0xf
	v_fmac_f32_dpp v49, v61, v37 row_ror:1 row_mask:0xf bank_mask:0xf
	v_rcp_f32_e32 v53, v53
	v_fmac_f32_dpp v50, v62, v38 row_ror:1 row_mask:0xf bank_mask:0xf
	v_fmac_f32_dpp v51, v63, v39 row_ror:1 row_mask:0xf bank_mask:0xf
	v_rcp_f32_e32 v54, v54
	v_fmac_f32_dpp v48, v60, v40 row_ror:2 row_mask:0xf bank_mask:0xf
	v_fmac_f32_dpp v49, v61, v41 row_ror:2 row_mask:0xf bank_mask:0xf
	v_rcp_f32_e32 v55, v55
	v_fmac_f32_dpp v50, v62, v42 row_ror:2 row_mask:0xf bank_mask:0xf
	v_fmac_f32_dpp v51, v63, v43 row_ror:2 row_mask:0xf bank_mask:0xf
	v_pk_mul_f32 v[44:45], v[44:45], v[52:53]
	v_pk_mul_f32 v[46:47], v[46:47], v[54:55]
	v_pk_mul_f32 v[44:45], v[48:49], v[44:45]
	v_pk_mul_f32 v[46:47], v[50:51], v[46:47]
	v_mov_b32_e32 v88, v166
	v_mov_b32_e32 v89, v167
	v_cvt_pk_bf16_f32 v90, v44, v45
	v_cvt_pk_bf16_f32 v91, v46, v47
	v_add_u32_e32 v58, 0x2c000, v234
	global_store_dwordx4 v58, v[88:91], s[18:19]
	v_pk_fma_f32 v[44:45], v[180:181], v[16:17], v[188:189]
	v_pk_fma_f32 v[46:47], v[182:183], v[18:19], v[190:191]
	v_pk_fma_f32 v[48:49], v[172:173], v[12:13], v[168:169]
	v_pk_fma_f32 v[50:51], v[174:175], v[14:15], v[170:171]
	v_fmac_f32_dpp v44, v16, v192 row_shr:1 row_mask:0xf bank_mask:0xf
	v_fmac_f32_dpp v45, v17, v193 row_shr:1 row_mask:0xf bank_mask:0xf
	v_fmac_f32_dpp v46, v18, v194 row_shr:1 row_mask:0xf bank_mask:0xf
	v_fmac_f32_dpp v47, v19, v195 row_shr:1 row_mask:0xf bank_mask:0xf
	v_fmac_f32_dpp v44, v16, v236 row_shr:2 row_mask:0xf bank_mask:0xf
	v_fmac_f32_dpp v45, v17, v237 row_shr:2 row_mask:0xf bank_mask:0xf
	v_fmac_f32_dpp v46, v18, v238 row_shr:2 row_mask:0xf bank_mask:0xf
	v_fmac_f32_dpp v47, v19, v239 row_shr:2 row_mask:0xf bank_mask:0xf
	v_fmac_f32_dpp v44, v24, v28 row_ror:1 row_mask:0xf bank_mask:0xf
	v_fmac_f32_dpp v45, v25, v29 row_ror:1 row_mask:0xf bank_mask:0xf
	v_fmac_f32_dpp v46, v26, v30 row_ror:1 row_mask:0xf bank_mask:0xf
	v_fmac_f32_dpp v47, v27, v31 row_ror:1 row_mask:0xf bank_mask:0xf
	v_fmac_f32_dpp v44, v24, v32 row_ror:2 row_mask:0xf bank_mask:0xf
	v_fmac_f32_dpp v45, v25, v33 row_ror:2 row_mask:0xf bank_mask:0xf
	v_fmac_f32_dpp v46, v26, v34 row_ror:2 row_mask:0xf bank_mask:0xf
	v_fmac_f32_dpp v47, v27, v35 row_ror:2 row_mask:0xf bank_mask:0xf
	v_pk_mul_f32 v[52:53], v[44:45], v[240:241] op_sel_hi:[1,0]
	v_pk_mul_f32 v[54:55], v[46:47], v[240:241] op_sel_hi:[1,0]
	v_exp_f32_e32 v52, v52
	v_fmac_f32_dpp v48, v12, v176 row_shr:1 row_mask:0xf bank_mask:0xf
	v_fmac_f32_dpp v49, v13, v177 row_shr:1 row_mask:0xf bank_mask:0xf
	v_exp_f32_e32 v53, v53
	v_fmac_f32_dpp v50, v14, v178 row_shr:1 row_mask:0xf bank_mask:0xf
	v_fmac_f32_dpp v51, v15, v179 row_shr:1 row_mask:0xf bank_mask:0xf
	v_exp_f32_e32 v54, v54
	v_fmac_f32_dpp v48, v12, v184 row_shr:2 row_mask:0xf bank_mask:0xf
	v_fmac_f32_dpp v49, v13, v185 row_shr:2 row_mask:0xf bank_mask:0xf
	v_exp_f32_e32 v55, v55
	v_fmac_f32_dpp v50, v14, v186 row_shr:2 row_mask:0xf bank_mask:0xf
	v_fmac_f32_dpp v51, v15, v187 row_shr:2 row_mask:0xf bank_mask:0xf
	v_pk_add_f32 v[52:53], v[52:53], v[240:241] op_sel:[0,1] op_sel_hi:[1,1]
	v_pk_add_f32 v[54:55], v[54:55], v[240:241] op_sel:[0,1] op_sel_hi:[1,1]
	v_rcp_f32_e32 v52, v52
	v_fmac_f32_dpp v48, v20, v36 row_ror:1 row_mask:0xf bank_mask:0xf
	v_fmac_f32_dpp v49, v21, v37 row_ror:1 row_mask:0xf bank_mask:0xf
	v_rcp_f32_e32 v53, v53
	v_fmac_f32_dpp v50, v22, v38 row_ror:1 row_mask:0xf bank_mask:0xf
	v_fmac_f32_dpp v51, v23, v39 row_ror:1 row_mask:0xf bank_mask:0xf
	v_rcp_f32_e32 v54, v54
	v_fmac_f32_dpp v48, v20, v40 row_ror:2 row_mask:0xf bank_mask:0xf
	v_fmac_f32_dpp v49, v21, v41 row_ror:2 row_mask:0xf bank_mask:0xf
	v_rcp_f32_e32 v55, v55
	v_fmac_f32_dpp v50, v22, v42 row_ror:2 row_mask:0xf bank_mask:0xf
	v_fmac_f32_dpp v51, v23, v43 row_ror:2 row_mask:0xf bank_mask:0xf
	v_pk_mul_f32 v[44:45], v[44:45], v[52:53]
	v_pk_mul_f32 v[46:47], v[46:47], v[54:55]
	v_pk_mul_f32 v[44:45], v[48:49], v[44:45]
	v_pk_mul_f32 v[46:47], v[50:51], v[46:47]
	v_mov_b32_e32 v124, v128
	v_mov_b32_e32 v125, v129
	v_cvt_pk_bf16_f32 v126, v44, v45
	v_cvt_pk_bf16_f32 v127, v46, v47
	v_add_u32_e32 v58, 0x58000, v234
	global_store_dwordx4 v58, v[124:127], s[18:19]
	v_pk_fma_f32 v[44:45], v[180:181], v[8:9], v[188:189]
	v_pk_fma_f32 v[46:47], v[182:183], v[10:11], v[190:191]
	v_pk_fma_f32 v[48:49], v[172:173], v[4:5], v[168:169]
	v_pk_fma_f32 v[50:51], v[174:175], v[6:7], v[170:171]
	v_fmac_f32_dpp v44, v8, v192 row_shr:1 row_mask:0xf bank_mask:0xf
	v_fmac_f32_dpp v45, v9, v193 row_shr:1 row_mask:0xf bank_mask:0xf
	v_fmac_f32_dpp v46, v10, v194 row_shr:1 row_mask:0xf bank_mask:0xf
	v_fmac_f32_dpp v47, v11, v195 row_shr:1 row_mask:0xf bank_mask:0xf
	v_fmac_f32_dpp v44, v8, v236 row_shr:2 row_mask:0xf bank_mask:0xf
	v_fmac_f32_dpp v45, v9, v237 row_shr:2 row_mask:0xf bank_mask:0xf
	v_fmac_f32_dpp v46, v10, v238 row_shr:2 row_mask:0xf bank_mask:0xf
	v_fmac_f32_dpp v47, v11, v239 row_shr:2 row_mask:0xf bank_mask:0xf
	v_fmac_f32_dpp v44, v16, v28 row_ror:1 row_mask:0xf bank_mask:0xf
	v_fmac_f32_dpp v45, v17, v29 row_ror:1 row_mask:0xf bank_mask:0xf
	v_fmac_f32_dpp v46, v18, v30 row_ror:1 row_mask:0xf bank_mask:0xf
	v_fmac_f32_dpp v47, v19, v31 row_ror:1 row_mask:0xf bank_mask:0xf
	v_fmac_f32_dpp v44, v16, v32 row_ror:2 row_mask:0xf bank_mask:0xf
	v_fmac_f32_dpp v45, v17, v33 row_ror:2 row_mask:0xf bank_mask:0xf
	v_fmac_f32_dpp v46, v18, v34 row_ror:2 row_mask:0xf bank_mask:0xf
	v_fmac_f32_dpp v47, v19, v35 row_ror:2 row_mask:0xf bank_mask:0xf
	v_pk_mul_f32 v[52:53], v[44:45], v[240:241] op_sel_hi:[1,0]
	v_pk_mul_f32 v[54:55], v[46:47], v[240:241] op_sel_hi:[1,0]
	v_exp_f32_e32 v52, v52
	v_fmac_f32_dpp v48, v4, v176 row_shr:1 row_mask:0xf bank_mask:0xf
	v_fmac_f32_dpp v49, v5, v177 row_shr:1 row_mask:0xf bank_mask:0xf
	v_exp_f32_e32 v53, v53
	v_fmac_f32_dpp v50, v6, v178 row_shr:1 row_mask:0xf bank_mask:0xf
	v_fmac_f32_dpp v51, v7, v179 row_shr:1 row_mask:0xf bank_mask:0xf
	v_exp_f32_e32 v54, v54
	v_fmac_f32_dpp v48, v4, v184 row_shr:2 row_mask:0xf bank_mask:0xf
	v_fmac_f32_dpp v49, v5, v185 row_shr:2 row_mask:0xf bank_mask:0xf
	v_exp_f32_e32 v55, v55
	v_fmac_f32_dpp v50, v6, v186 row_shr:2 row_mask:0xf bank_mask:0xf
	v_fmac_f32_dpp v51, v7, v187 row_shr:2 row_mask:0xf bank_mask:0xf
	v_pk_add_f32 v[52:53], v[52:53], v[240:241] op_sel:[0,1] op_sel_hi:[1,1]
	v_pk_add_f32 v[54:55], v[54:55], v[240:241] op_sel:[0,1] op_sel_hi:[1,1]
	v_rcp_f32_e32 v52, v52
	v_fmac_f32_dpp v48, v12, v36 row_ror:1 row_mask:0xf bank_mask:0xf
	v_fmac_f32_dpp v49, v13, v37 row_ror:1 row_mask:0xf bank_mask:0xf
	v_rcp_f32_e32 v53, v53
	v_fmac_f32_dpp v50, v14, v38 row_ror:1 row_mask:0xf bank_mask:0xf
	v_fmac_f32_dpp v51, v15, v39 row_ror:1 row_mask:0xf bank_mask:0xf
	v_rcp_f32_e32 v54, v54
	v_fmac_f32_dpp v48, v12, v40 row_ror:2 row_mask:0xf bank_mask:0xf
	v_fmac_f32_dpp v49, v13, v41 row_ror:2 row_mask:0xf bank_mask:0xf
	v_rcp_f32_e32 v55, v55
	v_fmac_f32_dpp v50, v14, v42 row_ror:2 row_mask:0xf bank_mask:0xf
	v_fmac_f32_dpp v51, v15, v43 row_ror:2 row_mask:0xf bank_mask:0xf
	v_pk_mul_f32 v[44:45], v[44:45], v[52:53]
	v_pk_mul_f32 v[46:47], v[46:47], v[54:55]
	v_pk_mul_f32 v[44:45], v[48:49], v[44:45]
	v_pk_mul_f32 v[46:47], v[50:51], v[46:47]
	v_mov_b32_e32 v88, v130
	v_mov_b32_e32 v89, v131
	v_cvt_pk_bf16_f32 v90, v44, v45
	v_cvt_pk_bf16_f32 v91, v46, v47
	v_add_u32_e32 v58, 0x84000, v234
	global_store_dwordx4 v58, v[88:91], s[18:19]
	s_cmp_eq_u32 s63, 0
	s_cbranch_scc1 .Leu_halo_skip_a1n1
	v_subrev_u32_e32 v58, 12, v56
	v_mul_u32_u24_e32 v58, 0xb000, v58
	v_lshl_add_u32 v58, v57, 5, v58
	s_mul_i32 s39, s12, 0x2c000
	s_lshl_b32 s40, s13, 9
	s_add_i32 s39, s39, s40
	s_lshl_b32 s40, s64, 2
	s_add_i32 s39, s39, s40
	s_add_u32 s20, s72, s39
	s_addc_u32 s21, s73, 0
	s_add_u32 s22, s20, 0x5800
	s_addc_u32 s23, s21, 0
	s_and_saveexec_b64 s[8:9], s[10:11]
	global_store_dwordx4 v58, v[8:11], s[20:21] offset:16
	global_store_dwordx4 v58, v[4:7], s[22:23] offset:16
	s_and_b32 s39, s12, 7
	s_cmp_lg_u32 s39, 7
	s_cbranch_scc1 .Leu_ffn_skip_a1n1
	v_subrev_u32_e32 v59, 14, v56
	v_mul_u32_u24_e32 v59, 0xb000, v59
	v_lshl_add_u32 v59, v57, 5, v59
	s_lshr_b32 s39, s12, 3
	s_mul_i32 s39, s39, 0x16000
	s_lshl_b32 s40, s13, 9
	s_add_i32 s39, s39, s40
	s_lshl_b32 s40, s64, 2
	s_add_i32 s39, s39, s40
	s_add_u32 s20, s28, s39
	s_addc_u32 s21, s29, 0
	s_add_u32 s22, s20, 0x5800
	s_addc_u32 s23, s21, 0
	global_store_dwordx4 v59, v[8:11], s[20:21] offset:16
	global_store_dwordx4 v59, v[4:7], s[22:23] offset:16
